# K|V|Q and conv in-projection K-loops: all 16 LDS-DMA loads per iteration in scalar-base form (no 64-bit VALU address adds left in those loops)
# speedup vs baseline: 1.0052x; 1.0030x over previous
.Lpadj_4:
	s_waitcnt vmcnt(8)
	s_waitcnt lgkmcnt(0)
	s_barrier
	v_mfma_f32_16x16x32_bf16 v[126:129], v[142:145], v[186:189], v[126:129]
	v_mfma_f32_16x16x32_bf16 v[122:125], v[162:165], v[186:189], v[122:125]
	v_mfma_f32_16x16x32_bf16 v[110:113], v[142:145], v[194:197], v[110:113]
	v_mfma_f32_16x16x32_bf16 v[106:109], v[162:165], v[194:197], v[106:109]
	v_mfma_f32_16x16x32_bf16 v[94:97], v[142:145], v[202:205], v[94:97]
	v_mfma_f32_16x16x32_bf16 v[90:93], v[162:165], v[202:205], v[90:93]
	v_mfma_f32_16x16x32_bf16 v[78:81], v[142:145], v[220:223], v[78:81]
	v_mfma_f32_16x16x32_bf16 v[74:77], v[162:165], v[220:223], v[74:77]
	v_mfma_f32_16x16x32_bf16 v[126:129], v[158:161], v[190:193], v[126:129]
	v_mfma_f32_16x16x32_bf16 v[122:125], v[166:169], v[190:193], v[122:125]
	v_mfma_f32_16x16x32_bf16 v[110:113], v[158:161], v[198:201], v[110:113]
	v_mfma_f32_16x16x32_bf16 v[106:109], v[166:169], v[198:201], v[106:109]
	v_mfma_f32_16x16x32_bf16 v[94:97], v[158:161], v[206:209], v[94:97]
	v_mfma_f32_16x16x32_bf16 v[90:93], v[166:169], v[206:209], v[90:93]
	v_mfma_f32_16x16x32_bf16 v[78:81], v[158:161], v[236:239], v[78:81]
	v_mfma_f32_16x16x32_bf16 v[74:77], v[166:169], v[236:239], v[74:77]
	v_mfma_f32_16x16x32_bf16 v[118:121], v[170:173], v[186:189], v[118:121]
	v_mfma_f32_16x16x32_bf16 v[114:117], v[178:181], v[186:189], v[114:117]
	v_mfma_f32_16x16x32_bf16 v[102:105], v[170:173], v[194:197], v[102:105]
	v_mfma_f32_16x16x32_bf16 v[98:101], v[178:181], v[194:197], v[98:101]
	v_mfma_f32_16x16x32_bf16 v[86:89], v[170:173], v[202:205], v[86:89]
	v_mfma_f32_16x16x32_bf16 v[82:85], v[178:181], v[202:205], v[82:85]
	v_mfma_f32_16x16x32_bf16 v[70:73], v[170:173], v[220:223], v[70:73]
	v_mfma_f32_16x16x32_bf16 v[66:69], v[178:181], v[220:223], v[66:69]
	v_mfma_f32_16x16x32_bf16 v[118:121], v[174:177], v[190:193], v[118:121]
	v_mfma_f32_16x16x32_bf16 v[114:117], v[182:185], v[190:193], v[114:117]
	v_mfma_f32_16x16x32_bf16 v[102:105], v[174:177], v[198:201], v[102:105]
	v_mfma_f32_16x16x32_bf16 v[98:101], v[182:185], v[198:201], v[98:101]
	v_mfma_f32_16x16x32_bf16 v[86:89], v[174:177], v[206:209], v[86:89]
	v_mfma_f32_16x16x32_bf16 v[82:85], v[182:185], v[206:209], v[82:85]
	v_mfma_f32_16x16x32_bf16 v[70:73], v[174:177], v[236:239], v[70:73]
	v_mfma_f32_16x16x32_bf16 v[66:69], v[182:185], v[236:239], v[66:69]
	s_barrier
	s_add_i32 s56, s56, s27
	s_mov_b32 m0, s56
	ds_read_b128 v[186:189], v157 offset:16384
	ds_read_b128 v[190:193], v157 offset:17408
	ds_read_b128 v[194:197], v157 offset:18432
	ds_read_b128 v[198:201], v157 offset:19456
	ds_read_b128 v[202:205], v157 offset:20480
	ds_read_b128 v[206:209], v157 offset:21504
	ds_read_b128 v[220:223], v157 offset:22528
	ds_read_b128 v[236:239], v157 offset:23552
	global_load_lds_dwordx4 v132, s[30:31]
	s_add_i32 m0, s56, 0x2000
	s_add_u32 s56, s30, 0x40000
	s_addc_u32 s57, s31, 0
	s_add_i32 s58, s58, s27
	global_load_lds_dwordx4 v136, s[30:31]
	s_mov_b32 m0, s58
	s_nop 0
	global_load_lds_dwordx4 v132, s[56:57]
	s_add_i32 m0, s58, 0x2000
	s_nop 0
	global_load_lds_dwordx4 v136, s[56:57]
	s_mov_b32 m0, s44
	s_nop 0
	global_load_lds_dwordx4 v130, s[34:35]
	s_mov_b32 m0, s45
	s_nop 0
	global_load_lds_dwordx4 v134, s[34:35]
	s_branch .Lpadj_5
	s_nop 0
	s_nop 0
	s_nop 0
	s_nop 0
	s_nop 0
	s_nop 0
	s_nop 0
	s_nop 0
	s_nop 0
	s_nop 0
	s_nop 0
	s_nop 0
	s_nop 0
	s_nop 0

.Lpadj_6:
	s_waitcnt vmcnt(8)
	s_waitcnt lgkmcnt(0)
	s_barrier
	v_mfma_f32_16x16x32_bf16 v[126:129], v[142:145], v[186:189], v[126:129]
	v_mfma_f32_16x16x32_bf16 v[122:125], v[162:165], v[186:189], v[122:125]
	v_mfma_f32_16x16x32_bf16 v[110:113], v[142:145], v[194:197], v[110:113]
	v_mfma_f32_16x16x32_bf16 v[106:109], v[162:165], v[194:197], v[106:109]
	v_mfma_f32_16x16x32_bf16 v[94:97], v[142:145], v[202:205], v[94:97]
	v_mfma_f32_16x16x32_bf16 v[90:93], v[162:165], v[202:205], v[90:93]
	v_mfma_f32_16x16x32_bf16 v[78:81], v[142:145], v[220:223], v[78:81]
	v_mfma_f32_16x16x32_bf16 v[74:77], v[162:165], v[220:223], v[74:77]
	v_mfma_f32_16x16x32_bf16 v[126:129], v[158:161], v[190:193], v[126:129]
	v_mfma_f32_16x16x32_bf16 v[122:125], v[166:169], v[190:193], v[122:125]
	v_mfma_f32_16x16x32_bf16 v[110:113], v[158:161], v[198:201], v[110:113]
	v_mfma_f32_16x16x32_bf16 v[106:109], v[166:169], v[198:201], v[106:109]
	v_mfma_f32_16x16x32_bf16 v[94:97], v[158:161], v[206:209], v[94:97]
	v_mfma_f32_16x16x32_bf16 v[90:93], v[166:169], v[206:209], v[90:93]
	v_mfma_f32_16x16x32_bf16 v[78:81], v[158:161], v[236:239], v[78:81]
	v_mfma_f32_16x16x32_bf16 v[74:77], v[166:169], v[236:239], v[74:77]
	v_mfma_f32_16x16x32_bf16 v[118:121], v[170:173], v[186:189], v[118:121]
	v_mfma_f32_16x16x32_bf16 v[114:117], v[178:181], v[186:189], v[114:117]
	v_mfma_f32_16x16x32_bf16 v[102:105], v[170:173], v[194:197], v[102:105]
	v_mfma_f32_16x16x32_bf16 v[98:101], v[178:181], v[194:197], v[98:101]
	v_mfma_f32_16x16x32_bf16 v[86:89], v[170:173], v[202:205], v[86:89]
	v_mfma_f32_16x16x32_bf16 v[82:85], v[178:181], v[202:205], v[82:85]
	v_mfma_f32_16x16x32_bf16 v[70:73], v[170:173], v[220:223], v[70:73]
	v_mfma_f32_16x16x32_bf16 v[66:69], v[178:181], v[220:223], v[66:69]
	v_mfma_f32_16x16x32_bf16 v[118:121], v[174:177], v[190:193], v[118:121]
	v_mfma_f32_16x16x32_bf16 v[114:117], v[182:185], v[190:193], v[114:117]
	v_mfma_f32_16x16x32_bf16 v[102:105], v[174:177], v[198:201], v[102:105]
	v_mfma_f32_16x16x32_bf16 v[98:101], v[182:185], v[198:201], v[98:101]
	v_mfma_f32_16x16x32_bf16 v[86:89], v[174:177], v[206:209], v[86:89]
	v_mfma_f32_16x16x32_bf16 v[82:85], v[182:185], v[206:209], v[82:85]
	v_mfma_f32_16x16x32_bf16 v[70:73], v[174:177], v[236:239], v[70:73]
	v_mfma_f32_16x16x32_bf16 v[66:69], v[182:185], v[236:239], v[66:69]
	s_barrier
	s_add_u32 s100, s34, 0xfffc0080
	s_addc_u32 s101, s35, -1
	s_add_u32 s30, s30, 0x80
	s_addc_u32 s31, s31, 0
	s_add_i32 s34, s56, s27
	s_mov_b32 m0, s34
	ds_read_b128 v[186:189], v157 offset:49152
	ds_read_b128 v[190:193], v157 offset:50176
	ds_read_b128 v[194:197], v157 offset:51200
	ds_read_b128 v[198:201], v157 offset:52224
	ds_read_b128 v[202:205], v157 offset:53248
	ds_read_b128 v[206:209], v157 offset:54272
	ds_read_b128 v[220:223], v157 offset:55296
	ds_read_b128 v[236:239], v157 offset:56320
	global_load_lds_dwordx4 v132, s[30:31]
	s_add_i32 m0, s34, 0x2000
	s_add_i32 s34, s57, s27
	global_load_lds_dwordx4 v136, s[30:31]
	s_add_u32 s30, s30, 0x40000
	s_addc_u32 s31, s31, 0
	s_mov_b32 m0, s34
	s_nop 0
	global_load_lds_dwordx4 v132, s[30:31]
	s_add_i32 m0, s34, 0x2000
	s_nop 0
	global_load_lds_dwordx4 v136, s[30:31]
	s_mov_b32 m0, s47
	s_nop 0
	global_load_lds_dwordx4 v130, s[100:101]
	s_mov_b32 m0, s48
	s_nop 0
	global_load_lds_dwordx4 v134, s[100:101]
	s_branch .Lpadj_7
	s_nop 0
	s_nop 0
	s_nop 0
	s_nop 0
	s_nop 0
	s_nop 0
	s_nop 0
	s_nop 0

.Lpadj_24:
	s_waitcnt vmcnt(8)
	s_waitcnt lgkmcnt(0)
	s_barrier
	v_mfma_f32_16x16x32_bf16 v[126:129], v[164:167], v[196:199], v[126:129]
	v_mfma_f32_16x16x32_bf16 v[122:125], v[172:175], v[196:199], v[122:125]
	v_mfma_f32_16x16x32_bf16 v[118:121], v[164:167], v[204:207], v[118:121]
	v_mfma_f32_16x16x32_bf16 v[114:117], v[172:175], v[204:207], v[114:117]
	v_mfma_f32_16x16x32_bf16 v[110:113], v[164:167], v[236:239], v[110:113]
	v_mfma_f32_16x16x32_bf16 v[106:109], v[172:175], v[236:239], v[106:109]
	v_mfma_f32_16x16x32_bf16 v[102:105], v[164:167], v[244:247], v[102:105]
	v_mfma_f32_16x16x32_bf16 v[98:101], v[172:175], v[244:247], v[98:101]
	v_mfma_f32_16x16x32_bf16 v[126:129], v[168:171], v[200:203], v[126:129]
	v_mfma_f32_16x16x32_bf16 v[122:125], v[176:179], v[200:203], v[122:125]
	v_mfma_f32_16x16x32_bf16 v[118:121], v[168:171], v[220:223], v[118:121]
	v_mfma_f32_16x16x32_bf16 v[114:117], v[176:179], v[220:223], v[114:117]
	v_mfma_f32_16x16x32_bf16 v[110:113], v[168:171], v[240:243], v[110:113]
	v_mfma_f32_16x16x32_bf16 v[106:109], v[176:179], v[240:243], v[106:109]
	v_mfma_f32_16x16x32_bf16 v[102:105], v[168:171], v[248:251], v[102:105]
	v_mfma_f32_16x16x32_bf16 v[98:101], v[176:179], v[248:251], v[98:101]
	v_mfma_f32_16x16x32_bf16 v[94:97], v[180:183], v[196:199], v[94:97]
	v_mfma_f32_16x16x32_bf16 v[90:93], v[188:191], v[196:199], v[90:93]
	v_mfma_f32_16x16x32_bf16 v[86:89], v[180:183], v[204:207], v[86:89]
	v_mfma_f32_16x16x32_bf16 v[82:85], v[188:191], v[204:207], v[82:85]
	v_mfma_f32_16x16x32_bf16 v[78:81], v[180:183], v[236:239], v[78:81]
	v_mfma_f32_16x16x32_bf16 v[74:77], v[188:191], v[236:239], v[74:77]
	v_mfma_f32_16x16x32_bf16 v[70:73], v[180:183], v[244:247], v[70:73]
	v_mfma_f32_16x16x32_bf16 v[66:69], v[188:191], v[244:247], v[66:69]
	v_mfma_f32_16x16x32_bf16 v[94:97], v[184:187], v[200:203], v[94:97]
	v_mfma_f32_16x16x32_bf16 v[90:93], v[192:195], v[200:203], v[90:93]
	v_mfma_f32_16x16x32_bf16 v[86:89], v[184:187], v[220:223], v[86:89]
	v_mfma_f32_16x16x32_bf16 v[82:85], v[192:195], v[220:223], v[82:85]
	v_mfma_f32_16x16x32_bf16 v[78:81], v[184:187], v[240:243], v[78:81]
	v_mfma_f32_16x16x32_bf16 v[74:77], v[192:195], v[240:243], v[74:77]
	v_mfma_f32_16x16x32_bf16 v[70:73], v[184:187], v[248:251], v[70:73]
	v_mfma_f32_16x16x32_bf16 v[66:69], v[192:195], v[248:251], v[66:69]
	s_barrier
	s_add_i32 s46, s46, s28
	s_mov_b32 m0, s46
	ds_read_b128 v[196:199], v162 offset:16384
	ds_read_b128 v[200:203], v162 offset:17408
	ds_read_b128 v[204:207], v162 offset:18432
	ds_read_b128 v[220:223], v162 offset:19456
	ds_read_b128 v[236:239], v162 offset:20480
	ds_read_b128 v[240:243], v162 offset:21504
	ds_read_b128 v[244:247], v162 offset:22528
	ds_read_b128 v[248:251], v162 offset:23552
	global_load_lds_dwordx4 v134, s[22:23]
	s_add_i32 m0, s46, 0x2000
	s_add_u32 s46, s22, 0x40000
	s_addc_u32 s47, s23, 0
	s_add_i32 s48, s48, s28
	global_load_lds_dwordx4 v130, s[22:23]
	s_mov_b32 m0, s48
	s_nop 0
	global_load_lds_dwordx4 v134, s[46:47]
	s_add_i32 m0, s48, 0x2000
	s_nop 0
	global_load_lds_dwordx4 v130, s[46:47]
	s_mov_b32 m0, s30
	s_nop 0
	global_load_lds_dwordx4 v136, s[24:25]
	s_mov_b32 m0, s31
	s_nop 0
	global_load_lds_dwordx4 v132, s[24:25]
	s_branch .Lpadj_25
	s_nop 0
	s_nop 0
	s_nop 0
	s_nop 0
	s_nop 0
	s_nop 0
	s_nop 0
	s_nop 0
	s_nop 0
	s_nop 0
	s_nop 0
	s_nop 0
	s_nop 0
	s_nop 0

.Lpadj_26:
	s_waitcnt vmcnt(8)
	s_waitcnt lgkmcnt(0)
	s_barrier
	v_mfma_f32_16x16x32_bf16 v[126:129], v[164:167], v[196:199], v[126:129]
	v_mfma_f32_16x16x32_bf16 v[122:125], v[172:175], v[196:199], v[122:125]
	v_mfma_f32_16x16x32_bf16 v[118:121], v[164:167], v[204:207], v[118:121]
	v_mfma_f32_16x16x32_bf16 v[114:117], v[172:175], v[204:207], v[114:117]
	v_mfma_f32_16x16x32_bf16 v[110:113], v[164:167], v[236:239], v[110:113]
	v_mfma_f32_16x16x32_bf16 v[106:109], v[172:175], v[236:239], v[106:109]
	v_mfma_f32_16x16x32_bf16 v[102:105], v[164:167], v[244:247], v[102:105]
	v_mfma_f32_16x16x32_bf16 v[98:101], v[172:175], v[244:247], v[98:101]
	v_mfma_f32_16x16x32_bf16 v[126:129], v[168:171], v[200:203], v[126:129]
	v_mfma_f32_16x16x32_bf16 v[122:125], v[176:179], v[200:203], v[122:125]
	v_mfma_f32_16x16x32_bf16 v[118:121], v[168:171], v[220:223], v[118:121]
	v_mfma_f32_16x16x32_bf16 v[114:117], v[176:179], v[220:223], v[114:117]
	v_mfma_f32_16x16x32_bf16 v[110:113], v[168:171], v[240:243], v[110:113]
	v_mfma_f32_16x16x32_bf16 v[106:109], v[176:179], v[240:243], v[106:109]
	v_mfma_f32_16x16x32_bf16 v[102:105], v[168:171], v[248:251], v[102:105]
	v_mfma_f32_16x16x32_bf16 v[98:101], v[176:179], v[248:251], v[98:101]
	v_mfma_f32_16x16x32_bf16 v[94:97], v[180:183], v[196:199], v[94:97]
	v_mfma_f32_16x16x32_bf16 v[90:93], v[188:191], v[196:199], v[90:93]
	v_mfma_f32_16x16x32_bf16 v[86:89], v[180:183], v[204:207], v[86:89]
	v_mfma_f32_16x16x32_bf16 v[82:85], v[188:191], v[204:207], v[82:85]
	v_mfma_f32_16x16x32_bf16 v[78:81], v[180:183], v[236:239], v[78:81]
	v_mfma_f32_16x16x32_bf16 v[74:77], v[188:191], v[236:239], v[74:77]
	v_mfma_f32_16x16x32_bf16 v[70:73], v[180:183], v[244:247], v[70:73]
	v_mfma_f32_16x16x32_bf16 v[66:69], v[188:191], v[244:247], v[66:69]
	v_mfma_f32_16x16x32_bf16 v[94:97], v[184:187], v[200:203], v[94:97]
	v_mfma_f32_16x16x32_bf16 v[90:93], v[192:195], v[200:203], v[90:93]
	v_mfma_f32_16x16x32_bf16 v[86:89], v[184:187], v[220:223], v[86:89]
	v_mfma_f32_16x16x32_bf16 v[82:85], v[192:195], v[220:223], v[82:85]
	v_mfma_f32_16x16x32_bf16 v[78:81], v[184:187], v[240:243], v[78:81]
	v_mfma_f32_16x16x32_bf16 v[74:77], v[192:195], v[240:243], v[74:77]
	v_mfma_f32_16x16x32_bf16 v[70:73], v[184:187], v[248:251], v[70:73]
	v_mfma_f32_16x16x32_bf16 v[66:69], v[192:195], v[248:251], v[66:69]
	s_barrier
	s_add_u32 s100, s24, 0xfffc0080
	s_addc_u32 s101, s25, -1
	s_add_u32 s22, s22, 0x80
	s_addc_u32 s23, s23, 0
	s_add_i32 s24, s46, s28
	s_mov_b32 m0, s24
	ds_read_b128 v[196:199], v162 offset:49152
	ds_read_b128 v[200:203], v162 offset:50176
	ds_read_b128 v[204:207], v162 offset:51200
	ds_read_b128 v[220:223], v162 offset:52224
	ds_read_b128 v[236:239], v162 offset:53248
	ds_read_b128 v[240:243], v162 offset:54272
	ds_read_b128 v[244:247], v162 offset:55296
	ds_read_b128 v[248:251], v162 offset:56320
	global_load_lds_dwordx4 v134, s[22:23]
	s_add_i32 m0, s24, 0x2000
	s_add_i32 s24, s47, s28
	global_load_lds_dwordx4 v130, s[22:23]
	s_add_u32 s22, s22, 0x40000
	s_addc_u32 s23, s23, 0
	s_mov_b32 m0, s24
	s_nop 0
	global_load_lds_dwordx4 v134, s[22:23]
	s_add_i32 m0, s24, 0x2000
	s_nop 0
	global_load_lds_dwordx4 v130, s[22:23]
	s_mov_b32 m0, s36
	s_nop 0
	global_load_lds_dwordx4 v136, s[100:101]
	s_mov_b32 m0, s37
	s_nop 0
	global_load_lds_dwordx4 v132, s[100:101]
	s_branch .Lpadj_27
	s_nop 0
	s_nop 0
	s_nop 0
	s_nop 0
	s_nop 0
	s_nop 0
	s_nop 0
	s_nop 0
